# phase 12: workgroups 128..255 (five tiles + conversion, a spare tile slot) start their tiles two s_sleep 127 later: their output bursts fall between those of workgroups 0..127
# speedup vs baseline: 1.0041x; 1.0041x over previous
.LBB0_1458:
	s_addk_i32 s10, 0x80
	s_ashr_i32 s4, s10, 31
	s_lshr_b32 s4, s4, 30
	s_add_i32 s4, s10, s4
	s_ashr_i32 s5, s4, 2
	s_lshl_b32 s4, s5, 6
	s_lshl_b32 s5, s5, 10
	s_sub_i32 s8, s11, s5
	v_or_b32_e32 v26, s4, v8
	s_ashr_i32 s9, s8, 31
	v_ashrrev_i32_e32 v27, 31, v26
	v_or_b32_e32 v28, 16, v26
	v_or_b32_e32 v30, 32, v26
	v_or_b32_e32 v32, 48, v26
	v_lshl_add_u64 v[34:35], s[8:9], 2, v[4:5]
	v_lshlrev_b64 v[26:27], 12, v[26:27]
	v_lshl_add_u64 v[36:37], v[34:35], 0, v[26:27]
	v_add_co_u32_e32 v58, vcc, s12, v36
	v_ashrrev_i32_e32 v29, 31, v28
	s_nop 0
	v_addc_co_u32_e32 v59, vcc, 0, v37, vcc
	v_add_co_u32_e32 v62, vcc, s13, v36
	v_ashrrev_i32_e32 v31, 31, v30
	s_nop 0
	v_addc_co_u32_e32 v63, vcc, 0, v37, vcc
	v_add_co_u32_e32 v66, vcc, s14, v36
	v_ashrrev_i32_e32 v33, 31, v32
	s_nop 0
	v_addc_co_u32_e32 v67, vcc, 0, v37, vcc
	v_lshlrev_b64 v[38:39], 12, v[28:29]
	v_lshlrev_b64 v[30:31], 12, v[30:31]
	v_lshlrev_b64 v[32:33], 12, v[32:33]
	v_add_co_u32_e32 v70, vcc, s15, v36
	global_load_dwordx4 v[26:29], v[36:37], off
	v_lshl_add_u64 v[60:61], v[34:35], 0, v[38:39]
	v_lshl_add_u64 v[64:65], v[34:35], 0, v[30:31]
	v_lshl_add_u64 v[68:69], v[34:35], 0, v[32:33]
	v_addc_co_u32_e32 v71, vcc, 0, v37, vcc
	global_load_dwordx4 v[30:33], v[58:59], off
	global_load_dwordx4 v[34:37], v[60:61], off
	global_load_dwordx4 v[38:41], v[62:63], off
	global_load_dwordx4 v[42:45], v[64:65], off
	global_load_dwordx4 v[46:49], v[66:67], off
	global_load_dwordx4 v[50:53], v[68:69], off
	global_load_dwordx4 v[54:57], v[70:71], off
	v_add_u32_e32 v25, s8, v146
	v_mad_i64_i32 v[58:59], s[8:9], v25, s16, v[6:7]
	s_ashr_i32 s5, s4, 31
	s_add_i32 s11, s11, 0x8000
	v_lshl_add_u64 v[58:59], s[4:5], 1, v[58:59]
	s_cmp_lt_i32 s10, 48
	v_lshl_add_u64 v[58:59], v[58:59], 0, v[2:3]
	s_waitcnt vmcnt(0)
	ds_write2_b32 v9, v26, v27 offset1:1
	ds_write2_b32 v9, v28, v29 offset0:2 offset1:3
	ds_write2_b32 v10, v30, v31 offset1:1
	ds_write2_b32 v11, v32, v33 offset1:1
	ds_write2_b32 v12, v34, v35 offset1:1
	ds_write2_b32 v13, v36, v37 offset1:1
	ds_write2_b32 v14, v38, v39 offset1:1
	ds_write2_b32 v15, v40, v41 offset1:1
	ds_write2_b32 v16, v42, v43 offset1:1
	ds_write2_b32 v17, v44, v45 offset1:1
	ds_write2_b32 v18, v46, v47 offset1:1
	ds_write2_b32 v19, v48, v49 offset1:1
	ds_write2_b32 v20, v50, v51 offset1:1
	ds_write2_b32 v21, v52, v53 offset1:1
	ds_write2_b32 v22, v54, v55 offset1:1
	ds_write2_b32 v23, v56, v57 offset1:1
	s_waitcnt lgkmcnt(0)
	s_barrier
	ds_read_b32 v25, v24
	ds_read_b32 v26, v24 offset:1028
	ds_read_b32 v27, v24 offset:2056
	ds_read_b32 v28, v24 offset:3084
	ds_read_b32 v29, v24 offset:4112
	ds_read_b32 v30, v24 offset:5140
	ds_read_b32 v31, v24 offset:6168
	ds_read_b32 v32, v24 offset:7196
	ds_read_b32 v33, v24 offset:8224
	ds_read_b32 v34, v24 offset:9252
	ds_read_b32 v35, v24 offset:10280
	ds_read_b32 v36, v24 offset:11308
	ds_read_b32 v37, v24 offset:12336
	ds_read_b32 v38, v24 offset:13364
	ds_read_b32 v39, v24 offset:14392
	ds_read_b32 v40, v24 offset:15420
	ds_read_b32 v41, v24 offset:16448
	ds_read_b32 v42, v24 offset:17476
	ds_read_b32 v43, v24 offset:18504
	ds_read_b32 v44, v24 offset:19532
	ds_read_b32 v45, v24 offset:20560
	ds_read_b32 v46, v24 offset:21588
	ds_read_b32 v47, v24 offset:22616
	ds_read_b32 v48, v24 offset:23644
	ds_read_b32 v49, v24 offset:24672
	ds_read_b32 v50, v24 offset:25700
	ds_read_b32 v51, v24 offset:26728
	ds_read_b32 v52, v24 offset:27756
	ds_read_b32 v53, v24 offset:28784
	ds_read_b32 v54, v24 offset:29812
	ds_read_b32 v55, v24 offset:30840
	ds_read_b32 v56, v24 offset:31868
	s_waitcnt lgkmcnt(14)
	v_cvt_pk_bf16_f32 v26, v25, v26
	v_cvt_pk_bf16_f32 v27, v27, v28
	v_cvt_pk_bf16_f32 v28, v29, v30
	v_cvt_pk_bf16_f32 v29, v31, v32
	v_cvt_pk_bf16_f32 v30, v33, v34
	v_cvt_pk_bf16_f32 v31, v35, v36
	v_cvt_pk_bf16_f32 v32, v37, v38
	v_cvt_pk_bf16_f32 v33, v39, v40
	v_cvt_pk_bf16_f32 v34, v41, v42
	s_waitcnt lgkmcnt(12)
	v_cvt_pk_bf16_f32 v35, v43, v44
	s_waitcnt lgkmcnt(10)
	v_cvt_pk_bf16_f32 v36, v45, v46
	s_waitcnt lgkmcnt(8)
	v_cvt_pk_bf16_f32 v37, v47, v48
	s_waitcnt lgkmcnt(6)
	v_cvt_pk_bf16_f32 v38, v49, v50
	s_waitcnt lgkmcnt(4)
	v_cvt_pk_bf16_f32 v39, v51, v52
	s_waitcnt lgkmcnt(2)
	v_cvt_pk_bf16_f32 v40, v53, v54
	s_waitcnt lgkmcnt(0)
	v_cvt_pk_bf16_f32 v41, v55, v56
	global_store_dwordx4 v[58:59], v[26:29], off
	global_store_dwordx4 v[58:59], v[30:33], off offset:16
	global_store_dwordx4 v[58:59], v[34:37], off offset:32
	global_store_dwordx4 v[58:59], v[38:41], off offset:48
	s_barrier
	s_cbranch_scc1 .LBB0_1458
	s_sleep 127
	s_sleep 127
